# v71 + W_branch and W_out transposes also moved from the prologue into the idle tail of each layer's mixer phase (one 64x64 item per wave)
# speedup vs baseline: 1.0283x; 1.0033x over previous
; #define GAS __attribute__((address_space(1)))
; __device__ __forceinline__ unsigned cvt_pk_bf16(float lo, float hi) { const f32x2 v = {lo, hi}; return __builtin_bit_cast(unsigned, __builtin_convertvector(v, bf16n2)); }
;     __device__ __forceinline__ int lane_() const { return lane_id(); }
; #define F_w_in F.in(8)
; __device__ __forceinline__ void p0_transpose_item(const GAS float* W, int K, int N, GAS bf16* WT, int item, int lane) {
;     const int nblk = N / 64, kb = item / nblk, nb = item - kb * nblk, r = lane >> 4, c4 = lane & 15;
;     const GAS float* src = W + (size_t)(64 * kb + 16 * r) * N + 64 * nb + 4 * c4;
;     f32x4 v[16];
; #pragma unroll
;     for (int i = 0; i < 16; ++i) v[i] = __builtin_nontemporal_load((const GAS f32x4*)(src + (size_t)i * N));
;     GAS bf16* dst = WT + (size_t)(64 * nb + 4 * c4) * K + 64 * kb + 16 * r;
; #pragma unroll
;     for (int j = 0; j < 4; ++j) { v4u a, b;
;         a.x = cvt_pk_bf16(v[0][j], v[1][j]); a.y = cvt_pk_bf16(v[2][j], v[3][j]); a.z = cvt_pk_bf16(v[4][j], v[5][j]); a.w = cvt_pk_bf16(v[6][j], v[7][j]);
;         b.x = cvt_pk_bf16(v[8][j], v[9][j]); b.y = cvt_pk_bf16(v[10][j], v[11][j]); b.z = cvt_pk_bf16(v[12][j], v[13][j]); b.w = cvt_pk_bf16(v[14][j], v[15][j]);
;         *(GAS v4u*)(dst + (size_t)j * K) = a; *(GAS v4u*)(dst + (size_t)j * K + 8) = b; }
; }
; __device__ __forceinline__ void phase_prologue(Frame& F) {
;     ...
;     for (int it = gw; it < NITEMS; it += NGW) {
;         int r = it;
;         if (r < 2 * I_IN) { const int l = r / I_IN; p0_transpose_item(F_w_in + (size_t)l * D * NPROJ, D, NPROJ, win_t + (size_t)l * NPROJ * D, r % I_IN, F.lane_()); continue; } r -= 2 * I_IN;
;         if (r < 6 * I_SQ) { const int m = r / I_SQ; p0_transpose_item(F_w_branch + (size_t)m * D * D, D, D, wbr_t + (size_t)m * D * D, r % I_SQ, F.lane_()); continue; } r -= 6 * I_SQ;
;         if (r < 2 * I_SQ) { const int m = r / I_SQ; p0_transpose_item(F_w_out + (size_t)m * D * D, D, D, wout_t + (size_t)m * D * D, r % I_SQ, F.lane_()); continue; } r -= 2 * I_SQ;
;         { const int m = r / I_PL; p0_transpose_item(F_w_pool + (size_t)m * 65536, 256, 256, wpool_t + (size_t)m * 65536, r % I_PL, F.lane_()); }
.LBB0_17:
	s_cmpk_gt_i32 s59, 0x19ff
	s_mov_b64 s[10:11], -1
	s_cbranch_scc0 .LBB0_27
	s_cmpk_lt_u32 s59, 0x2200
	s_cbranch_scc1 .LBB0_16
	s_cmpk_gt_u32 s59, 0x1fff
	s_cbranch_scc0 .LBB0_24
	s_cmpk_gt_u32 s59, 0x21ff
	s_cbranch_scc0 .LBB0_21
	v_mov_b32_e32 v0, s26
	ds_read_b64 v[2:3], v0
	s_add_i32 s8, s59, 0xffffde00
	s_lshr_b32 s8, s8, 4
	s_lshl_b64 s[10:11], s[8:9], 18
	v_mov_b32_e32 v0, v1
	s_waitcnt lgkmcnt(0)
	v_readfirstlane_b32 s12, v2
	v_readfirstlane_b32 s13, v3
	s_add_u32 s12, s12, s10
	s_addc_u32 s13, s13, s11
	s_lshl_b64 s[10:11], s[8:9], 17
	v_mbcnt_lo_u32_b32 v0, -1, v0
	s_add_u32 s10, s20, s10
	v_mbcnt_hi_u32_b32 v0, -1, v0
	s_addc_u32 s11, s21, s11
	s_and_b32 s14, s22, 0xc0
	v_and_b32_e32 v66, -16, v0
	v_add_u32_e32 v2, s14, v66
	v_ashrrev_i32_e32 v3, 31, v2
	v_lshlrev_b64 v[2:3], 10, v[2:3]
	v_lshl_add_u64 v[2:3], s[12:13], 0, v[2:3]
	s_and_b32 s12, s24, 0xc0
	v_lshlrev_b32_e32 v0, 2, v0
	s_lshl_b32 s8, s12, 2
	v_and_b32_e32 v68, 60, v0
	v_lshl_add_u64 v[2:3], v[2:3], 0, s[8:9]
	v_lshlrev_b32_e32 v0, 2, v68
	v_lshl_add_u64 v[42:43], v[2:3], 0, v[0:1]
	v_add_co_u32_e32 v30, vcc, s27, v42
	global_load_dwordx4 v[2:5], v[42:43], off nt
	global_load_dwordx4 v[6:9], v[42:43], off offset:1024 nt
	global_load_dwordx4 v[10:13], v[42:43], off offset:2048 nt
	global_load_dwordx4 v[14:17], v[42:43], off offset:3072 nt
	v_addc_co_u32_e32 v31, vcc, 0, v43, vcc
	v_add_co_u32_e32 v46, vcc, s28, v42
	v_or_b32_e32 v0, s12, v68
	s_nop 0
	v_addc_co_u32_e32 v47, vcc, 0, v43, vcc
	v_add_co_u32_e32 v62, vcc, s29, v42
	global_load_dwordx4 v[18:21], v[46:47], off offset:-4096 nt
	global_load_dwordx4 v[22:25], v[30:31], off offset:1024 nt
	global_load_dwordx4 v[26:29], v[30:31], off offset:2048 nt
	s_nop 0
	global_load_dwordx4 v[30:33], v[30:31], off offset:3072 nt
	s_nop 0
	global_load_dwordx4 v[34:37], v[46:47], off nt
	global_load_dwordx4 v[38:41], v[46:47], off offset:1024 nt
	v_addc_co_u32_e32 v63, vcc, 0, v43, vcc
	global_load_dwordx4 v[42:45], v[46:47], off offset:2048 nt
	s_nop 0
	global_load_dwordx4 v[46:49], v[46:47], off offset:3072 nt
	s_nop 0
	global_load_dwordx4 v[50:53], v[62:63], off offset:3072 nt
	global_load_dwordx4 v[54:57], v[62:63], off nt
	global_load_dwordx4 v[58:61], v[62:63], off offset:1024 nt
	s_nop 0
	global_load_dwordx4 v[62:65], v[62:63], off offset:2048 nt
	v_lshlrev_b32_e32 v0, 9, v0
	s_lshl_b32 s8, s14, 1
	v_lshl_add_u64 v[68:69], s[10:11], 0, v[0:1]
	v_ashrrev_i32_e32 v67, 31, v66
	v_lshl_add_u64 v[68:69], v[68:69], 0, s[8:9]
	v_lshl_add_u64 v[74:75], v[66:67], 1, v[68:69]
	s_mov_b64 s[10:11], 0
	s_waitcnt vmcnt(14)
	v_cvt_pk_bf16_f32 v2, v2, v6
	v_cvt_pk_bf16_f32 v6, v3, v7
	v_cvt_pk_bf16_f32 v66, v4, v8
	v_cvt_pk_bf16_f32 v70, v5, v9
	s_waitcnt vmcnt(12)
	v_cvt_pk_bf16_f32 v3, v10, v14
	v_cvt_pk_bf16_f32 v71, v13, v17
	v_cvt_pk_bf16_f32 v7, v11, v15
	v_cvt_pk_bf16_f32 v67, v12, v16
	s_waitcnt vmcnt(10)
	v_cvt_pk_bf16_f32 v4, v18, v22
	v_cvt_pk_bf16_f32 v72, v21, v25
	s_waitcnt vmcnt(8)
	v_cvt_pk_bf16_f32 v5, v26, v30
	v_cvt_pk_bf16_f32 v73, v29, v33
	v_cvt_pk_bf16_f32 v8, v19, v23
	v_cvt_pk_bf16_f32 v68, v20, v24
	s_waitcnt vmcnt(6)
	v_cvt_pk_bf16_f32 v10, v34, v38
	v_cvt_pk_bf16_f32 v9, v27, v31
	v_cvt_pk_bf16_f32 v69, v28, v32
	v_cvt_pk_bf16_f32 v14, v35, v39
	v_cvt_pk_bf16_f32 v18, v36, v40
	v_cvt_pk_bf16_f32 v22, v37, v41
	s_waitcnt vmcnt(4)
	v_cvt_pk_bf16_f32 v11, v42, v46
	s_waitcnt vmcnt(1)
	v_cvt_pk_bf16_f32 v12, v54, v58
	s_waitcnt vmcnt(0)
	v_cvt_pk_bf16_f32 v13, v62, v50
	v_cvt_pk_bf16_f32 v15, v43, v47
	v_cvt_pk_bf16_f32 v16, v55, v59
	v_cvt_pk_bf16_f32 v17, v63, v51
	v_cvt_pk_bf16_f32 v19, v44, v48
	v_cvt_pk_bf16_f32 v20, v56, v60
	v_cvt_pk_bf16_f32 v21, v64, v52
	v_cvt_pk_bf16_f32 v23, v45, v49
	global_store_dwordx4 v[74:75], v[2:5], off
	global_store_dwordx4 v[74:75], v[10:13], off offset:16
	global_store_dwordx4 v[74:75], v[6:9], off offset:512
	global_store_dwordx4 v[74:75], v[14:17], off offset:528
	global_store_dwordx4 v[74:75], v[66:69], off offset:1024
	global_store_dwordx4 v[74:75], v[18:21], off offset:1040
	v_cvt_pk_bf16_f32 v24, v57, v61
	v_cvt_pk_bf16_f32 v25, v65, v53
	global_store_dwordx4 v[74:75], v[70:73], off offset:1536
	global_store_dwordx4 v[74:75], v[22:25], off offset:1552

;     __device__ __forceinline__ int lane_() const { return lane_id(); }
; #define F_w_in F.in(8)
; __device__ __forceinline__ void phase_prologue(Frame& F) {
;     ...
;     for (int it = gw; it < NITEMS; it += NGW) {
;         int r = it;
;         if (r < 2 * I_IN) { const int l = r / I_IN; p0_transpose_item(F_w_in + (size_t)l * D * NPROJ, D, NPROJ, win_t + (size_t)l * NPROJ * D, r % I_IN, F.lane_()); continue; } r -= 2 * I_IN;
;         if (r < 6 * I_SQ) { const int m = r / I_SQ; p0_transpose_item(F_w_branch + (size_t)m * D * D, D, D, wbr_t + (size_t)m * D * D, r % I_SQ, F.lane_()); continue; } r -= 6 * I_SQ;
;         if (r < 2 * I_SQ) { const int m = r / I_SQ; p0_transpose_item(F_w_out + (size_t)m * D * D, D, D, wout_t + (size_t)m * D * D, r % I_SQ, F.lane_()); continue; } r -= 2 * I_SQ;
;         { const int m = r / I_PL; p0_transpose_item(F_w_pool + (size_t)m * 65536, 256, 256, wpool_t + (size_t)m * 65536, r % I_PL, F.lane_()); }
;     }
.LBB0_881:
	s_cmpk_lt_u32 s101, 64
	s_cbranch_scc1 .Ldv_done
	v_mbcnt_lo_u32_b32 v182, -1, 0
	v_mbcnt_hi_u32_b32 v182, -1, v182
	v_mov_b32_e32 v188, 0x27d40
	v_mov_b32_e32 v190, s18
	ds_read_b64 v[188:189], v188
	ds_read_b64 v[190:191], v190
	v_mov_b32_e32 v192, 0x27d78
	v_mov_b32_e32 v194, 0x27d80
	ds_read_b64 v[192:193], v192
	ds_read_b64 v[194:195], v194
	v_lshrrev_b32_e32 v183, 4, v182
	v_and_b32_e32 v184, 15, v182
	v_lshlrev_b32_e32 v186, 13, v184
	v_lshl_add_u32 v186, v183, 5, v186
	v_add_u32_e32 v187, 0x1000, v186
	s_waitcnt lgkmcnt(0)
	v_readfirstlane_b32 s16, v188
	v_readfirstlane_b32 s17, v189
	v_readfirstlane_b32 s14, v190
	v_readfirstlane_b32 s15, v191
	v_readfirstlane_b32 s70, v192
	v_readfirstlane_b32 s71, v193
	v_readfirstlane_b32 s88, v194
	v_readfirstlane_b32 s89, v195
	s_sub_u32 s58, s101, 64
	s_lshl_b32 s58, s58, 3
	s_lshr_b32 s8, s95, 10
	s_add_u32 s58, s58, s8
	v_readlane_b32 s59, v240, 7
	s_cmp_lg_u32 s59, 0
	s_cbranch_scc1 .Ldw_sq
	v_mul_u32_u24_e32 v185, 0xd0000, v183
	v_lshl_add_u32 v185, v184, 4, v185
	s_add_u32 s16, s16, 0x3400000
	s_addc_u32 s17, s17, 0
	s_add_u32 s64, s14, 0x1c00000
	s_addc_u32 s65, s15, 0
	s_mov_b32 s61, s58
	s_branch .Ldv_first

; #define GAS __attribute__((address_space(1)))
; __device__ __forceinline__ unsigned cvt_pk_bf16(float lo, float hi) { const f32x2 v = {lo, hi}; return __builtin_bit_cast(unsigned, __builtin_convertvector(v, bf16n2)); }
;     __device__ __forceinline__ int lane_() const { return lane_id(); }
; #define F_w_in F.in(8)
; __device__ __forceinline__ void p0_transpose_item(const GAS float* W, int K, int N, GAS bf16* WT, int item, int lane) {
;     const int nblk = N / 64, kb = item / nblk, nb = item - kb * nblk, r = lane >> 4, c4 = lane & 15;
;     const GAS float* src = W + (size_t)(64 * kb + 16 * r) * N + 64 * nb + 4 * c4;
;     f32x4 v[16];
; #pragma unroll
;     for (int i = 0; i < 16; ++i) v[i] = __builtin_nontemporal_load((const GAS f32x4*)(src + (size_t)i * N));
;     GAS bf16* dst = WT + (size_t)(64 * nb + 4 * c4) * K + 64 * kb + 16 * r;
; #pragma unroll
;     for (int j = 0; j < 4; ++j) { v4u a, b;
;         a.x = cvt_pk_bf16(v[0][j], v[1][j]); a.y = cvt_pk_bf16(v[2][j], v[3][j]); a.z = cvt_pk_bf16(v[4][j], v[5][j]); a.w = cvt_pk_bf16(v[6][j], v[7][j]);
;         b.x = cvt_pk_bf16(v[8][j], v[9][j]); b.y = cvt_pk_bf16(v[10][j], v[11][j]); b.z = cvt_pk_bf16(v[12][j], v[13][j]); b.w = cvt_pk_bf16(v[14][j], v[15][j]);
;         *(GAS v4u*)(dst + (size_t)j * K) = a; *(GAS v4u*)(dst + (size_t)j * K + 8) = b; }
; }
; __device__ __forceinline__ void phase_prologue(Frame& F) {
;     ...
;         if (r < 2 * I_IN) { const int l = r / I_IN; p0_transpose_item(F_w_in + (size_t)l * D * NPROJ, D, NPROJ, win_t + (size_t)l * NPROJ * D, r % I_IN, F.lane_()); continue; } r -= 2 * I_IN;
;         if (r < 6 * I_SQ) { const int m = r / I_SQ; p0_transpose_item(F_w_branch + (size_t)m * D * D, D, D, wbr_t + (size_t)m * D * D, r % I_SQ, F.lane_()); continue; } r -= 6 * I_SQ;
;         if (r < 2 * I_SQ) { const int m = r / I_SQ; p0_transpose_item(F_w_out + (size_t)m * D * D, D, D, wout_t + (size_t)m * D * D, r % I_SQ, F.lane_()); continue; } r -= 2 * I_SQ;
.Ldv_first:
	s_cmpk_gt_u32 s61, 0xcff
	s_cbranch_scc1 .Ldw_sq
	s_mul_i32 s8, s61, 0x4ec5
	s_lshr_b32 s8, s8, 22
	s_mul_i32 s9, s8, 0xd0
	s_sub_u32 s9, s61, s9
	s_mul_i32 s20, s8, 0x340000
	s_lshl_b32 s32, s9, 8
	s_add_u32 s20, s20, s32
	s_add_u32 s66, s16, s20
	s_addc_u32 s67, s17, 0
	s_mov_b64 s[68:69], s[64:65]
	global_load_dwordx4 v[80:83], v185, s[66:67] nt
	s_add_u32 s66, s66, 0xd000
	s_addc_u32 s67, s67, 0
	global_load_dwordx4 v[84:87], v185, s[66:67] nt
	s_add_u32 s66, s66, 0xd000
	s_addc_u32 s67, s67, 0
	global_load_dwordx4 v[88:91], v185, s[66:67] nt
	s_add_u32 s66, s66, 0xd000
	s_addc_u32 s67, s67, 0
	global_load_dwordx4 v[92:95], v185, s[66:67] nt
	s_add_u32 s66, s66, 0xd000
	s_addc_u32 s67, s67, 0
	global_load_dwordx4 v[96:99], v185, s[66:67] nt
	s_add_u32 s66, s66, 0xd000
	s_addc_u32 s67, s67, 0
	global_load_dwordx4 v[100:103], v185, s[66:67] nt
	s_add_u32 s66, s66, 0xd000
	s_addc_u32 s67, s67, 0
	global_load_dwordx4 v[104:107], v185, s[66:67] nt
	s_add_u32 s66, s66, 0xd000
	s_addc_u32 s67, s67, 0
	global_load_dwordx4 v[108:111], v185, s[66:67] nt
	s_add_u32 s66, s66, 0xd000
	s_addc_u32 s67, s67, 0
	global_load_dwordx4 v[128:131], v185, s[66:67] nt
	s_add_u32 s66, s66, 0xd000
	s_addc_u32 s67, s67, 0
	global_load_dwordx4 v[132:135], v185, s[66:67] nt
	s_add_u32 s66, s66, 0xd000
	s_addc_u32 s67, s67, 0
	global_load_dwordx4 v[136:139], v185, s[66:67] nt
	s_add_u32 s66, s66, 0xd000
	s_addc_u32 s67, s67, 0
	global_load_dwordx4 v[140:143], v185, s[66:67] nt
	s_add_u32 s66, s66, 0xd000
	s_addc_u32 s67, s67, 0
	global_load_dwordx4 v[144:147], v185, s[66:67] nt
	s_add_u32 s66, s66, 0xd000
	s_addc_u32 s67, s67, 0
	global_load_dwordx4 v[152:155], v185, s[66:67] nt
	s_add_u32 s66, s66, 0xd000
	s_addc_u32 s67, s67, 0
	global_load_dwordx4 v[156:159], v185, s[66:67] nt
	s_add_u32 s66, s66, 0xd000
	s_addc_u32 s67, s67, 0
	global_load_dwordx4 v[160:163], v185, s[66:67] nt
	s_lshl_b32 s20, s9, 17
	s_lshl_b32 s32, s8, 7
	s_add_u32 s20, s20, s32
	s_add_u32 s68, s68, s20
	s_addc_u32 s69, s69, 0
	s_waitcnt vmcnt(0)
	v_cvt_pk_bf16_f32 v164, v80, v84
	v_cvt_pk_bf16_f32 v165, v88, v92
	v_cvt_pk_bf16_f32 v166, v96, v100
	v_cvt_pk_bf16_f32 v167, v104, v108
	v_cvt_pk_bf16_f32 v168, v128, v132
	v_cvt_pk_bf16_f32 v169, v136, v140
	v_cvt_pk_bf16_f32 v170, v144, v152
	v_cvt_pk_bf16_f32 v171, v156, v160
	global_store_dwordx4 v186, v[164:167], s[68:69]
	global_store_dwordx4 v186, v[168:171], s[68:69] offset:16
	v_cvt_pk_bf16_f32 v192, v81, v85
	v_cvt_pk_bf16_f32 v193, v89, v93
	v_cvt_pk_bf16_f32 v194, v97, v101
	v_cvt_pk_bf16_f32 v195, v105, v109
	v_cvt_pk_bf16_f32 v196, v129, v133
	v_cvt_pk_bf16_f32 v197, v137, v141
	v_cvt_pk_bf16_f32 v198, v145, v153
	v_cvt_pk_bf16_f32 v199, v157, v161
	global_store_dwordx4 v186, v[192:195], s[68:69] offset:2048
	global_store_dwordx4 v186, v[196:199], s[68:69] offset:2064
	v_cvt_pk_bf16_f32 v164, v82, v86
	v_cvt_pk_bf16_f32 v165, v90, v94
	v_cvt_pk_bf16_f32 v166, v98, v102
	v_cvt_pk_bf16_f32 v167, v106, v110
	v_cvt_pk_bf16_f32 v168, v130, v134
	v_cvt_pk_bf16_f32 v169, v138, v142
	v_cvt_pk_bf16_f32 v170, v146, v154
	v_cvt_pk_bf16_f32 v171, v158, v162
	global_store_dwordx4 v187, v[164:167], s[68:69]
	global_store_dwordx4 v187, v[168:171], s[68:69] offset:16
	v_cvt_pk_bf16_f32 v192, v83, v87
	v_cvt_pk_bf16_f32 v193, v91, v95
	v_cvt_pk_bf16_f32 v194, v99, v103
	v_cvt_pk_bf16_f32 v195, v107, v111
	v_cvt_pk_bf16_f32 v196, v131, v135
	v_cvt_pk_bf16_f32 v197, v139, v143
	v_cvt_pk_bf16_f32 v198, v147, v155
	v_cvt_pk_bf16_f32 v199, v159, v163
	global_store_dwordx4 v187, v[192:195], s[68:69] offset:2048
	global_store_dwordx4 v187, v[196:199], s[68:69] offset:2064
	s_branch .Ldv_next
.Ldw_sq:
	s_cmpk_gt_u32 s58, 0x3ff
	s_cbranch_scc1 .Ldv_done
	v_lshlrev_b32_e32 v185, 16, v183
	v_lshl_add_u32 v185, v184, 4, v185
	s_cmp_lg_u32 s59, 0
	s_cselect_b32 s61, 1, 0
	s_cmpk_gt_u32 s58, 0x2ff
	s_cbranch_scc1 .Ldw_out
	s_mul_i32 s8, s61, 3
	s_lshr_b32 s9, s58, 8
	s_add_u32 s8, s8, s9
	s_mov_b64 s[66:67], s[70:71]
	s_add_u32 s68, s14, 0x3600000
	s_addc_u32 s69, s15, 0
	s_branch .Ldw_go
; #define GAS __attribute__((address_space(1)))
; __device__ __forceinline__ unsigned cvt_pk_bf16(float lo, float hi) { const f32x2 v = {lo, hi}; return __builtin_bit_cast(unsigned, __builtin_convertvector(v, bf16n2)); }
;     __device__ __forceinline__ int lane_() const { return lane_id(); }
; __device__ __forceinline__ void p0_transpose_item(const GAS float* W, int K, int N, GAS bf16* WT, int item, int lane) {
;     const int nblk = N / 64, kb = item / nblk, nb = item - kb * nblk, r = lane >> 4, c4 = lane & 15;
;     const GAS float* src = W + (size_t)(64 * kb + 16 * r) * N + 64 * nb + 4 * c4;
;     f32x4 v[16];
; #pragma unroll
;     for (int i = 0; i < 16; ++i) v[i] = __builtin_nontemporal_load((const GAS f32x4*)(src + (size_t)i * N));
;     GAS bf16* dst = WT + (size_t)(64 * nb + 4 * c4) * K + 64 * kb + 16 * r;
; #pragma unroll
;     for (int j = 0; j < 4; ++j) { v4u a, b;
;         a.x = cvt_pk_bf16(v[0][j], v[1][j]); a.y = cvt_pk_bf16(v[2][j], v[3][j]); a.z = cvt_pk_bf16(v[4][j], v[5][j]); a.w = cvt_pk_bf16(v[6][j], v[7][j]);
;         b.x = cvt_pk_bf16(v[8][j], v[9][j]); b.y = cvt_pk_bf16(v[10][j], v[11][j]); b.z = cvt_pk_bf16(v[12][j], v[13][j]); b.w = cvt_pk_bf16(v[14][j], v[15][j]);
;         *(GAS v4u*)(dst + (size_t)j * K) = a; *(GAS v4u*)(dst + (size_t)j * K + 8) = b; }
; }
; __device__ __forceinline__ void phase_prologue(Frame& F) {
;     ...
;         if (r < 6 * I_SQ) { const int m = r / I_SQ; p0_transpose_item(F_w_branch + (size_t)m * D * D, D, D, wbr_t + (size_t)m * D * D, r % I_SQ, F.lane_()); continue; } r -= 6 * I_SQ;
;         if (r < 2 * I_SQ) { const int m = r / I_SQ; p0_transpose_item(F_w_out + (size_t)m * D * D, D, D, wout_t + (size_t)m * D * D, r % I_SQ, F.lane_()); continue; } r -= 2 * I_SQ;
.Ldw_out:
	s_mov_b32 s8, s61
	s_mov_b64 s[66:67], s[88:89]
	s_add_u32 s68, s14, 0x4200000
	s_addc_u32 s69, s15, 0
.Ldw_go:
	s_lshl_b32 s9, s8, 22
	s_add_u32 s66, s66, s9
	s_addc_u32 s67, s67, 0
	s_lshl_b32 s9, s8, 21
	s_add_u32 s68, s68, s9
	s_addc_u32 s69, s69, 0
	s_bfe_u32 s8, s58, 0x40004
	s_and_b32 s9, s58, 15
	s_lshl_b32 s20, s8, 18
	s_lshl_b32 s32, s9, 8
	s_add_u32 s20, s20, s32
	s_add_u32 s66, s66, s20
	s_addc_u32 s67, s67, 0
	global_load_dwordx4 v[80:83], v185, s[66:67] nt
	s_add_u32 s66, s66, 0x1000
	s_addc_u32 s67, s67, 0
	global_load_dwordx4 v[84:87], v185, s[66:67] nt
	s_add_u32 s66, s66, 0x1000
	s_addc_u32 s67, s67, 0
	global_load_dwordx4 v[88:91], v185, s[66:67] nt
	s_add_u32 s66, s66, 0x1000
	s_addc_u32 s67, s67, 0
	global_load_dwordx4 v[92:95], v185, s[66:67] nt
	s_add_u32 s66, s66, 0x1000
	s_addc_u32 s67, s67, 0
	global_load_dwordx4 v[96:99], v185, s[66:67] nt
	s_add_u32 s66, s66, 0x1000
	s_addc_u32 s67, s67, 0
	global_load_dwordx4 v[100:103], v185, s[66:67] nt
	s_add_u32 s66, s66, 0x1000
	s_addc_u32 s67, s67, 0
	global_load_dwordx4 v[104:107], v185, s[66:67] nt
	s_add_u32 s66, s66, 0x1000
	s_addc_u32 s67, s67, 0
	global_load_dwordx4 v[108:111], v185, s[66:67] nt
	s_add_u32 s66, s66, 0x1000
	s_addc_u32 s67, s67, 0
	global_load_dwordx4 v[128:131], v185, s[66:67] nt
	s_add_u32 s66, s66, 0x1000
	s_addc_u32 s67, s67, 0
	global_load_dwordx4 v[132:135], v185, s[66:67] nt
	s_add_u32 s66, s66, 0x1000
	s_addc_u32 s67, s67, 0
	global_load_dwordx4 v[136:139], v185, s[66:67] nt
	s_add_u32 s66, s66, 0x1000
	s_addc_u32 s67, s67, 0
	global_load_dwordx4 v[140:143], v185, s[66:67] nt
	s_add_u32 s66, s66, 0x1000
	s_addc_u32 s67, s67, 0
	global_load_dwordx4 v[144:147], v185, s[66:67] nt
	s_add_u32 s66, s66, 0x1000
	s_addc_u32 s67, s67, 0
	global_load_dwordx4 v[152:155], v185, s[66:67] nt
	s_add_u32 s66, s66, 0x1000
	s_addc_u32 s67, s67, 0
	global_load_dwordx4 v[156:159], v185, s[66:67] nt
	s_add_u32 s66, s66, 0x1000
	s_addc_u32 s67, s67, 0
	global_load_dwordx4 v[160:163], v185, s[66:67] nt
	s_lshl_b32 s20, s9, 17
	s_lshl_b32 s32, s8, 7
	s_add_u32 s20, s20, s32
	s_add_u32 s68, s68, s20
	s_addc_u32 s69, s69, 0
	s_waitcnt vmcnt(0)
	v_cvt_pk_bf16_f32 v164, v80, v84
	v_cvt_pk_bf16_f32 v165, v88, v92
	v_cvt_pk_bf16_f32 v166, v96, v100
	v_cvt_pk_bf16_f32 v167, v104, v108
	v_cvt_pk_bf16_f32 v168, v128, v132
	v_cvt_pk_bf16_f32 v169, v136, v140
	v_cvt_pk_bf16_f32 v170, v144, v152
	v_cvt_pk_bf16_f32 v171, v156, v160
	global_store_dwordx4 v186, v[164:167], s[68:69]
	global_store_dwordx4 v186, v[168:171], s[68:69] offset:16
	v_cvt_pk_bf16_f32 v192, v81, v85
	v_cvt_pk_bf16_f32 v193, v89, v93
	v_cvt_pk_bf16_f32 v194, v97, v101
	v_cvt_pk_bf16_f32 v195, v105, v109
	v_cvt_pk_bf16_f32 v196, v129, v133
	v_cvt_pk_bf16_f32 v197, v137, v141
	v_cvt_pk_bf16_f32 v198, v145, v153
	v_cvt_pk_bf16_f32 v199, v157, v161
	global_store_dwordx4 v186, v[192:195], s[68:69] offset:2048
	global_store_dwordx4 v186, v[196:199], s[68:69] offset:2064
	v_cvt_pk_bf16_f32 v164, v82, v86
	v_cvt_pk_bf16_f32 v165, v90, v94
	v_cvt_pk_bf16_f32 v166, v98, v102
	v_cvt_pk_bf16_f32 v167, v106, v110
	v_cvt_pk_bf16_f32 v168, v130, v134
	v_cvt_pk_bf16_f32 v169, v138, v142
	v_cvt_pk_bf16_f32 v170, v146, v154
	v_cvt_pk_bf16_f32 v171, v158, v162
	global_store_dwordx4 v187, v[164:167], s[68:69]
	global_store_dwordx4 v187, v[168:171], s[68:69] offset:16
	v_cvt_pk_bf16_f32 v192, v83, v87
	v_cvt_pk_bf16_f32 v193, v91, v95
	v_cvt_pk_bf16_f32 v194, v99, v103
	v_cvt_pk_bf16_f32 v195, v107, v111
	v_cvt_pk_bf16_f32 v196, v131, v135
	v_cvt_pk_bf16_f32 v197, v139, v143
	v_cvt_pk_bf16_f32 v198, v147, v155
	v_cvt_pk_bf16_f32 v199, v159, v163
	global_store_dwordx4 v187, v[192:195], s[68:69] offset:2048
	global_store_dwordx4 v187, v[196:199], s[68:69] offset:2064
